# row_pre: sample item split into 1-row items on waves 0-3, no per-row VMEM drain, DOWN loads issued with X loads
# speedup vs baseline: 1.0043x; 1.0038x over previous
; __device__ __forceinline__ unsigned char* WSP() { return (unsigned char*)IN(41); }
; __device__ __forceinline__ int TID() { int t = threadIdx.x; asm volatile("" : "+v"(t)); return t; }
; __device__ __forceinline__ int BID() { int b = blockIdx.x; asm volatile("" : "+s"(b)); return b; }
; __device__ __forceinline__ int GSZ() { int g = gridDim.x; asm volatile("" : "+s"(g)); return g; }
; __device__ __forceinline__ int rfl(int v) { return __builtin_amdgcn_readfirstlane(v); }
; __device__ __forceinline__ void row_pre(const Params& p, int layer) {
;     const int tid_ = TID(), lane = tid_ & 63, wave_ = rfl(tid_ >> 6), bid_ = BID(), gw = bid_ * 8 + wave_, ngw = GSZ() * 8;
;     unsigned char* ws = WSP();
;     const bf16_t* Xold = (const bf16_t*)(ws + ((layer & 1) ? WS_XA : WS_XB));
;     bf16_t* Xnew = (bf16_t*)(ws + ((layer & 1) ? WS_XB : WS_XA));
;     const bf16_t* DOWN = (const bf16_t*)(ws + WS_MIX);
;     if (layer > 0) presum_sample_rows((bf16_t*)(ws + WS_MIX), bid_, tid_);
;     const float* gpost = IN(10) + (size_t)(layer - 1) * D;
;     const float* gpre = IN(7) + (size_t)layer * D;
;     const bool odd = layer & 1;
;     const int o = layer >> 1;
;     const int nit = (MP / 4 - gw + ngw - 1) / ngw;
;     for (int it_ = 0; it_ <= nit; ++it_) {
;         int item = gw + it_ * ngw;
;         if (it_ == nit) { if (wave_ != 0 || bid_ >= MS / 4) break; item = MP / 4 + bid_; }
;         const int m0 = item * 4;
;         const int t0 = m0 < MP ? (m0 & (SEQ - 1)) : ((m0 - MP) & (DSEQ - 1));
;         const int b = m0 < MP ? (m0 >> 12) : ((m0 - MP) >> 3);
;         const int Lseq = m0 < MP ? SEQ : DSEQ;
;         f32x4 hp[8];
;         const int rstart = (odd && t0 > 0) ? -1 : 0;
.LBB0_624:
	s_ashr_i32 s2, s10, 6
	s_ashr_i32 s100, s10, 6
	s_lshl_b32 s22, s12, 3
	s_add_i32 s22, s22, s2
	s_lshl_b32 s23, s11, 3
	s_and_b64 s[2:3], s[8:9], exec
	s_mov_b32 s2, 0xaa00000
	s_cselect_b32 s2, s2, 0x6800000
	v_writelane_b32 v234, s2, 26
	s_abs_i32 s2, s23
	v_cvt_f32_u32_e32 v0, s2
	s_sub_i32 s13, 0, s2
	s_sub_i32 s3, s23, s22
	s_addk_i32 s3, 0x7ff
	v_rcp_iflag_f32_e32 v0, v0
	s_xor_b32 s11, s3, s23
	s_abs_i32 s3, s3
	s_ashr_i32 s11, s11, 31
	v_mul_f32_e32 v0, 0x4f7ffffe, v0
	v_cvt_u32_f32_e32 v0, v0
	s_movk_i32 s5, 0x50
	s_mov_b32 s4, 56
	v_readfirstlane_b32 s16, v0
	s_mul_i32 s13, s13, s16
	s_mul_hi_u32 s13, s16, s13
	s_add_i32 s16, s16, s13
	s_mul_hi_u32 s13, s3, s16
	s_mul_i32 s16, s13, s2
	s_sub_i32 s3, s3, s16
	s_add_i32 s16, s13, 1
	s_sub_i32 s17, s3, s2
	s_cmp_ge_u32 s3, s2
	s_cselect_b32 s13, s16, s13
	s_cselect_b32 s3, s17, s3
	s_add_i32 s16, s13, 1
	s_cmp_ge_u32 s3, s2
	s_cselect_b32 s2, s16, s13
	s_xor_b32 s2, s2, s11
	s_sub_i32 s24, s2, s11
	s_cmp_lt_i32 s24, 0
	s_cbranch_scc1 .LBB0_688
	s_xor_b64 s[2:3], s[8:9], -1
	s_ashr_i32 s11, s5, 31
	s_add_u32 s16, s0, s5
	s_addc_u32 s17, s1, s11
	s_and_b64 s[18:19], s[8:9], exec
	s_mov_b32 s5, 0xaa00000
	s_cselect_b32 s5, 0x6800000, s5
	s_waitcnt lgkmcnt(0)
	s_add_u32 s18, s14, s5
	s_addc_u32 s19, s15, 0
	v_readlane_b32 s5, v234, 26
	v_readlane_b32 s30, v234, 19
	s_add_u32 s20, s14, s5
	v_readlane_b32 s31, v234, 20
	s_addc_u32 s21, s15, 0
	s_lshr_b64 s[26:27], s[30:31], 1
	s_lshr_b32 s5, s31, 1
	s_mul_i32 s5, s5, 0xc000
	s_mul_hi_u32 s11, s26, 0xc000
	s_add_i32 s34, s11, s5
	s_lshr_b32 s52, s30, 1
	s_ashr_i32 s5, s4, 31
	s_add_u32 s4, s0, s4
	s_addc_u32 s5, s1, s5
	s_load_dwordx2 s[4:5], s[4:5], 0x0
	s_nop 0
	s_load_dwordx2 s[16:17], s[16:17], 0x0
	s_lshl_b32 s11, s30, 13
	s_mul_i32 s35, s26, 0xc000
	s_mov_b32 s26, s30
	s_waitcnt lgkmcnt(0)
	s_add_u32 s4, s4, s11
	s_addc_u32 s5, s5, 0
	s_ashr_i32 s27, s30, 31
	s_lshl_b64 s[26:27], s[26:27], 13
	s_add_u32 s16, s16, s26
	s_addc_u32 s17, s17, s27
	v_lshlrev_b32_e32 v0, 2, v6
	s_cmp_lt_u32 s10, 0x100
	v_and_b32_e32 v72, 0xfc, v0
	s_cselect_b64 s[10:11], -1, 0
	s_cmp_lt_i32 s12, 64
	v_lshlrev_b32_e32 v2, 1, v72
	v_lshlrev_b32_e32 v4, 2, v72
	v_mov_b32_e32 v5, v3
	s_cselect_b64 s[26:27], -1, 0
	v_lshl_add_u64 v[0:1], s[14:15], 0, v[2:3]
	v_lshl_add_u64 v[82:83], s[4:5], 0, v[4:5]
	s_mov_b64 s[4:5], 0xec00000
	s_and_b64 s[10:11], s[10:11], s[26:27]
	s_add_i32 s26, s12, 0x800
	s_lshl_b64 s[12:13], s[52:53], 18
	v_lshl_add_u64 v[84:85], v[0:1], 0, s[4:5]
	s_lshl_b64 s[4:5], s[52:53], 16
	s_add_u32 s27, s4, 0x25c2000
	s_addc_u32 s28, s5, 0
	s_lshl_b64 s[4:5], s[52:53], 12
	s_add_u32 s30, s4, 0x25c0000
	s_addc_u32 s31, s5, 0
	s_movk_i32 s4, 0xf000
	v_lshl_add_u64 v[8:9], s[16:17], 0, v[4:5]
	s_mov_b32 s5, -1
	v_lshl_add_u64 v[86:87], v[8:9], 0, s[4:5]
	s_movk_i32 s4, 0xf400
	s_mov_b32 s5, -1
	v_lshl_add_u64 v[88:89], v[8:9], 0, s[4:5]
	s_movk_i32 s4, 0xf800
	s_mov_b32 s5, -1
	v_lshl_add_u64 v[90:91], v[8:9], 0, s[4:5]
	s_movk_i32 s4, 0xfc00
	s_mov_b32 s5, -1
	v_lshl_add_u64 v[74:75], s[18:19], 0, v[2:3]
	s_mov_b64 s[18:19], 0x10d00000
	v_lshl_add_u64 v[92:93], v[8:9], 0, s[4:5]
	s_mov_b64 s[4:5], 0x1400
	v_lshl_add_u64 v[76:77], v[0:1], 0, s[18:19]
	s_movk_i32 s16, 0xe000
	v_lshl_add_u64 v[96:97], v[82:83], 0, s[4:5]
	s_mov_b64 s[4:5], 0x1800
	v_and_b32_e32 v0, 63, v6
	s_mov_b32 s17, -1
	v_lshl_add_u64 v[80:81], s[20:21], 0, v[2:3]
	v_lshl_add_u64 v[98:99], v[82:83], 0, s[4:5]
	s_mov_b64 s[4:5], 0x1c00
	v_lshlrev_b32_e32 v2, 3, v0
	s_mov_b32 s25, 0
	v_lshl_add_u64 v[78:79], v[8:9], 0, s[16:17]
	v_lshl_add_u64 v[94:95], v[82:83], 0, s[56:57]
	v_lshl_add_u64 v[100:101], v[82:83], 0, s[4:5]
	v_lshl_or_b32 v102, v0, 4, s35
	v_mov_b32_e32 v103, s34
	v_lshl_add_u64 v[104:105], s[14:15], 0, v[2:3]
	s_andn2_b64 vcc, exec, s[40:41]
	s_cbranch_vccnz .Lrp_nopre
	global_load_dwordx4 v[196:199], v[78:79], off
	global_load_dwordx4 v[200:203], v[78:79], off offset:1024
	global_load_dwordx4 v[204:207], v[78:79], off offset:2048
	global_load_dwordx4 v[208:211], v[78:79], off offset:3072
	global_load_dwordx4 v[212:215], v[86:87], off
	global_load_dwordx4 v[216:219], v[88:89], off
	global_load_dwordx4 v[220:223], v[90:91], off
	global_load_dwordx4 v[224:227], v[92:93], off

; __device__ __forceinline__ void row_pre(const Params& p, int layer) {
;     ...
;         int item = gw + it_ * ngw;
;         if (it_ == nit) { if (wave_ != 0 || bid_ >= MS / 4) break; item = MP / 4 + bid_; }
;         const int m0 = item * 4;
;         const int t0 = m0 < MP ? (m0 & (SEQ - 1)) : ((m0 - MP) & (DSEQ - 1));
;         const int b = m0 < MP ? (m0 >> 12) : ((m0 - MP) >> 3);
;         const int Lseq = m0 < MP ? SEQ : DSEQ;
;         f32x4 hp[8];
;         const int rstart = (odd && t0 > 0) ? -1 : 0;
;         if (odd && t0 == 0) {
;             if (m0 < MP) {
; #pragma unroll
;                 for (int j = 0; j < 8; ++j) hp[j] = (f32x4){0.f, 0.f, 0.f, 0.f};
;             } else row_load(IN(6) + ((size_t)o * 32 + b) * D, lane, hp);
;         }
.LBB0_628:
	s_cmp_lg_u32 s25, s24
	s_cselect_b64 s[14:15], -1, 0
	s_or_b64 s[4:5], s[14:15], s[10:11]
	s_andn2_b64 vcc, exec, s[4:5]
	s_mov_b64 s[4:5], -1
	s_cbranch_vccnz .LBB0_627
	s_mul_i32 s4, s25, s23
	s_add_i32 s16, s4, s22
	s_and_b64 s[4:5], s[14:15], exec
	s_cselect_b32 s16, s16, s26
	s_cselect_b32 s17, 0, s100
	s_cselect_b32 s101, 2, -1
	s_lshl_b32 s34, s16, 2
	s_add_i32 s34, s34, s17
	s_cmpk_gt_i32 s16, 0x7ff
	s_cselect_b64 s[14:15], -1, 0
	s_cmpk_lt_i32 s16, 0x800
	s_cselect_b64 s[4:5], -1, 0
	s_and_b64 s[18:19], s[4:5], exec
	s_cselect_b32 s17, 0xffc, 7
	s_and_b32 s35, s17, s34
	s_add_i32 s17, s34, 0xffffe000
	s_lshr_b32 s52, s17, 3
	s_cmp_eq_u32 s35, 0
	s_cselect_b64 s[18:19], -1, 0
	s_and_b64 s[18:19], s[8:9], s[18:19]
	s_andn2_b64 vcc, exec, s[18:19]
	s_cbranch_vccnz .LBB0_633
	s_andn2_b64 vcc, exec, s[14:15]
	s_cbranch_vccnz .LBB0_632
	s_mov_b32 s14, 48
	s_ashr_i32 s15, s14, 31
	s_add_u32 s14, s0, s14
	s_addc_u32 s15, s1, s15
	s_load_dwordx2 s[14:15], s[14:15], 0x0
	v_lshlrev_b32_e32 v2, 2, v72
	s_waitcnt lgkmcnt(0)
	s_add_u32 s17, s14, s12
	s_addc_u32 s18, s15, s13
	s_lshl_b64 s[14:15], s[52:53], 13
	s_add_u32 s14, s17, s14
	s_addc_u32 s15, s18, s15
	v_lshl_add_u64 v[0:1], s[14:15], 0, v[2:3]
	v_add_co_u32_e32 v0, vcc, 0x1000, v0
	global_load_dwordx4 v[32:35], v2, s[14:15]
	global_load_dwordx4 v[28:31], v2, s[14:15] offset:1024
	global_load_dwordx4 v[24:27], v2, s[14:15] offset:2048
	global_load_dwordx4 v[16:19], v2, s[14:15] offset:3072
	v_addc_co_u32_e32 v1, vcc, 0, v1, vcc
	global_load_dwordx4 v[20:23], v[0:1], off
	global_load_dwordx4 v[12:15], v[0:1], off offset:1024
	global_load_dwordx4 v[8:11], v[0:1], off offset:2048
	global_load_dwordx4 v[4:7], v[0:1], off offset:3072
	s_branch .LBB0_633

; __device__ __forceinline__ void row_load_bf16(const bf16_t* p, int lane, f32x4 (&v)[8]) {
; #pragma unroll
;     for (int j = 0; j < 8; ++j) { const u32x2 r = *(const u32x2*)(p + 256 * j + 4 * lane);
;         v[j][0] = __builtin_bit_cast(float, r.x << 16); v[j][1] = __builtin_bit_cast(float, r.x & 0xffff0000u); v[j][2] = __builtin_bit_cast(float, r.y << 16); v[j][3] = __builtin_bit_cast(float, r.y & 0xffff0000u); }
; __device__ __forceinline__ void row_pre(const Params& p, int layer) {
;     ...
;         for (int r = rstart; r < 4; ++r) {
;             const int m = m0 + r;
;             f32x4 x[8];
;             xrow_load(Xold, layer == 0, m, lane, x);
;             if (layer > 0) {
;                 f32x4 dn[8]; row_load_bf16(DOWN + (size_t)m * D, lane, dn);
.LBB0_634:
	s_ashr_i32 s17, s16, 31
	s_lshl_b64 s[4:5], s[16:17], 12
	v_lshl_add_u64 v[36:37], v[74:75], 0, s[4:5]
	global_load_dwordx2 v[38:39], v[36:37], off
	global_load_dwordx2 v[40:41], v[36:37], off offset:512
	global_load_dwordx2 v[42:43], v[36:37], off offset:1024
	global_load_dwordx2 v[44:45], v[36:37], off offset:1536
	global_load_dwordx2 v[46:47], v[36:37], off offset:2048
	global_load_dwordx2 v[68:69], v[36:37], off offset:2560
	global_load_dwordx2 v[70:71], v[36:37], off offset:3072
	global_load_dwordx2 v[106:107], v[36:37], off offset:3584
	v_lshl_add_u64 v[162:163], v[76:77], 0, s[4:5]
	global_load_dwordx2 v[230:231], v[162:163], off
	global_load_dwordx2 v[112:113], v[162:163], off offset:512
	global_load_dwordx2 v[114:115], v[162:163], off offset:1024
	global_load_dwordx2 v[232:233], v[162:163], off offset:1536
	global_load_dwordx2 v[124:125], v[162:163], off offset:2048
	global_load_dwordx2 v[142:143], v[162:163], off offset:2560
	global_load_dwordx2 v[144:145], v[162:163], off offset:3072
	global_load_dwordx2 v[228:229], v[162:163], off offset:3584
	s_waitcnt vmcnt(15)
	v_lshlrev_b32_e32 v64, 16, v38
	v_and_b32_e32 v65, 0xffff0000, v38
	v_lshlrev_b32_e32 v66, 16, v39
	v_and_b32_e32 v67, 0xffff0000, v39
	s_waitcnt vmcnt(14)
	v_lshlrev_b32_e32 v60, 16, v40
	v_and_b32_e32 v61, 0xffff0000, v40
	v_lshlrev_b32_e32 v62, 16, v41
	v_and_b32_e32 v63, 0xffff0000, v41
	s_waitcnt vmcnt(13)
	v_lshlrev_b32_e32 v56, 16, v42
	v_and_b32_e32 v57, 0xffff0000, v42
	v_lshlrev_b32_e32 v58, 16, v43
	v_and_b32_e32 v59, 0xffff0000, v43
	s_waitcnt vmcnt(12)
	v_lshlrev_b32_e32 v48, 16, v44
	v_and_b32_e32 v49, 0xffff0000, v44
	v_lshlrev_b32_e32 v50, 16, v45
	v_and_b32_e32 v51, 0xffff0000, v45
	s_waitcnt vmcnt(11)
	v_lshlrev_b32_e32 v52, 16, v46
	v_and_b32_e32 v53, 0xffff0000, v46
	v_lshlrev_b32_e32 v54, 16, v47
	v_and_b32_e32 v55, 0xffff0000, v47
	s_waitcnt vmcnt(10)
	v_lshlrev_b32_e32 v44, 16, v68
	v_and_b32_e32 v45, 0xffff0000, v68
	v_lshlrev_b32_e32 v46, 16, v69
	v_and_b32_e32 v47, 0xffff0000, v69
	s_waitcnt vmcnt(9)
	v_lshlrev_b32_e32 v40, 16, v70
	v_and_b32_e32 v41, 0xffff0000, v70
	v_lshlrev_b32_e32 v42, 16, v71
	v_and_b32_e32 v43, 0xffff0000, v71
	s_waitcnt vmcnt(8)
	v_lshlrev_b32_e32 v36, 16, v106
	v_and_b32_e32 v37, 0xffff0000, v106
	v_lshlrev_b32_e32 v38, 16, v107
	v_and_b32_e32 v39, 0xffff0000, v107
	s_cbranch_execz .LBB0_636
	s_branch .LBB0_641

; __device__ __forceinline__ void row_load_bf16(const bf16_t* p, int lane, f32x4 (&v)[8]) {
; #pragma unroll
;     for (int j = 0; j < 8; ++j) { const u32x2 r = *(const u32x2*)(p + 256 * j + 4 * lane);
;         v[j][0] = __builtin_bit_cast(float, r.x << 16); v[j][1] = __builtin_bit_cast(float, r.x & 0xffff0000u); v[j][2] = __builtin_bit_cast(float, r.y << 16); v[j][3] = __builtin_bit_cast(float, r.y & 0xffff0000u); }
; }
; __device__ __forceinline__ float row_rstd(const f32x4 (&v)[8]) {
;     float s = 0.f;
; #pragma unroll
;     for (int j = 0; j < 8; ++j) s += (v[j][0] * v[j][0] + v[j][1] * v[j][1]) + (v[j][2] * v[j][2] + v[j][3] * v[j][3]);
;     return rsqrtf(wave_sum(s) * (1.f / D) + 1e-6f);
; __device__ __forceinline__ void row_pre(const Params& p, int layer) {
;     ...
;                 f32x4 dn[8]; row_load_bf16(DOWN + (size_t)m * D, lane, dn);
;                 const float rs = row_rstd(dn);
.LBB0_640:
	s_ashr_i32 s17, s20, 31
	s_add_u32 s18, s0, s20
	s_addc_u32 s19, s1, s17
	s_load_dwordx2 s[18:19], s[18:19], 0x0
	s_lshl_b64 s[4:5], s[4:5], 13
	v_lshlrev_b32_e32 v2, 2, v72
	s_waitcnt lgkmcnt(0)
	s_add_u32 s4, s18, s4
	s_addc_u32 s5, s19, s5
	v_lshl_add_u64 v[36:37], s[4:5], 0, v[2:3]
	v_add_co_u32_e32 v36, vcc, s55, v36
	global_load_dwordx4 v[64:67], v2, s[4:5]
	global_load_dwordx4 v[60:63], v2, s[4:5] offset:1024
	global_load_dwordx4 v[56:59], v2, s[4:5] offset:2048
	global_load_dwordx4 v[48:51], v2, s[4:5] offset:3072
	v_addc_co_u32_e32 v37, vcc, 0, v37, vcc
	global_load_dwordx4 v[52:55], v[36:37], off
	global_load_dwordx4 v[44:47], v[36:37], off offset:1024
	global_load_dwordx4 v[40:43], v[36:37], off offset:2048
	s_nop 0
	global_load_dwordx4 v[36:39], v[36:37], off offset:3072
.LBB0_641:
	s_andn2_b64 vcc, exec, s[40:41]
	s_cbranch_vccnz .LBB0_662
	s_cmp_lt_i32 s37, 0
	s_waitcnt vmcnt(7)
	v_and_b32_e32 v141, 0xffff0000, v231
	v_and_b32_e32 v139, 0xffff0000, v230
	v_lshlrev_b32_e32 v140, 16, v231
	v_mul_f32_e32 v2, v141, v141
	s_waitcnt vmcnt(4)
	v_lshlrev_b32_e32 v121, 16, v232
	v_and_b32_e32 v119, 0xffff0000, v232
	v_lshlrev_b32_e32 v116, 16, v233
	v_and_b32_e32 v117, 0xffff0000, v233
	s_waitcnt vmcnt(0)
	v_lshlrev_b32_e32 v111, 16, v228
	v_and_b32_e32 v109, 0xffff0000, v228
	v_lshlrev_b32_e32 v106, 16, v229
	v_and_b32_e32 v107, 0xffff0000, v229
	v_lshlrev_b32_e32 v138, 16, v230
	v_pk_fma_f32 v[68:69], v[140:141], v[140:141], v[2:3] op_sel_hi:[1,1,0]
	v_and_b32_e32 v137, 0xffff0000, v113
	v_and_b32_e32 v136, 0xffff0000, v112
	v_mul_f32_e32 v2, v139, v139
	v_lshlrev_b32_e32 v131, 16, v113
	v_lshlrev_b32_e32 v130, 16, v112
	v_pk_mul_f32 v[70:71], v[136:137], v[136:137]
	v_pk_fma_f32 v[112:113], v[138:139], v[138:139], v[2:3] op_sel_hi:[1,1,0]
	v_pk_fma_f32 v[70:71], v[130:131], v[130:131], v[70:71]
	v_lshlrev_b32_e32 v126, 16, v114
	v_and_b32_e32 v127, 0xffff0000, v114
	v_lshlrev_b32_e32 v128, 16, v115
	v_and_b32_e32 v129, 0xffff0000, v115
	v_mov_b32_e32 v120, v112
	v_mov_b32_e32 v114, v68
	v_mov_b32_e32 v115, v121
	v_mul_f32_e32 v1, v119, v119
	v_pk_add_f32 v[68:69], v[112:113], v[68:69]
	v_pk_mul_f32 v[112:113], v[120:121], v[114:115]
	v_pk_add_f32 v[70:71], v[70:71], v[70:71] op_sel:[0,1] op_sel_hi:[1,0]
	v_mov_b32_e32 v69, v113
	v_mov_b32_e32 v71, v1
	v_mul_f32_e32 v2, v127, v127
	v_pk_add_f32 v[68:69], v[68:69], v[70:71]
	v_pk_fma_f32 v[70:71], v[126:127], v[126:127], v[2:3] op_sel_hi:[1,1,0]
	v_mul_f32_e32 v2, v129, v129
	v_mul_f32_e32 v73, v116, v116
	v_mul_f32_e32 v108, v117, v117
	v_pk_fma_f32 v[112:113], v[128:129], v[128:129], v[2:3] op_sel_hi:[1,1,0]
	v_mov_b32_e32 v71, v73
	v_mov_b32_e32 v113, v108
	v_pk_add_f32 v[70:71], v[70:71], v[112:113]
	v_lshlrev_b32_e32 v123, 16, v125
	v_lshlrev_b32_e32 v122, 16, v124
	v_and_b32_e32 v125, 0xffff0000, v125
	v_and_b32_e32 v124, 0xffff0000, v124
	v_pk_add_f32 v[158:159], v[68:69], v[70:71]
	v_pk_mul_f32 v[68:69], v[124:125], v[124:125]
	v_and_b32_e32 v115, 0xffff0000, v143
	v_pk_fma_f32 v[68:69], v[122:123], v[122:123], v[68:69]
	v_and_b32_e32 v114, 0xffff0000, v142
	v_pk_add_f32 v[160:161], v[68:69], v[68:69] op_sel:[0,1] op_sel_hi:[1,0]
	v_lshlrev_b32_e32 v113, 16, v143
	v_lshlrev_b32_e32 v112, 16, v142
	v_pk_mul_f32 v[68:69], v[114:115], v[114:115]
	v_lshlrev_b32_e32 v70, 16, v145
	v_pk_fma_f32 v[142:143], v[112:113], v[112:113], v[68:69]
	v_lshlrev_b32_e32 v68, 16, v144
	v_and_b32_e32 v69, 0xffff0000, v144
	v_and_b32_e32 v71, 0xffff0000, v145
	v_pk_add_f32 v[144:145], v[158:159], v[158:159] op_sel:[0,1] op_sel_hi:[1,0]
	v_mov_b32_e32 v158, v160
	v_mov_b32_e32 v110, v144
	v_mov_b32_e32 v159, v111
	v_mul_f32_e32 v1, v109, v109
	v_pk_add_f32 v[144:145], v[144:145], v[160:161]
	v_pk_mul_f32 v[158:159], v[110:111], v[158:159]
	v_pk_add_f32 v[142:143], v[142:143], v[142:143] op_sel:[0,1] op_sel_hi:[1,0]
	v_mov_b32_e32 v145, v159
	v_mov_b32_e32 v143, v1
	v_mul_f32_e32 v2, v69, v69
	v_pk_add_f32 v[142:143], v[144:145], v[142:143]
	v_pk_fma_f32 v[144:145], v[68:69], v[68:69], v[2:3] op_sel_hi:[1,1,0]
	v_mul_f32_e32 v2, v71, v71
	v_mul_f32_e32 v73, v106, v106
	v_mul_f32_e32 v108, v107, v107
	v_pk_fma_f32 v[158:159], v[70:71], v[70:71], v[2:3] op_sel_hi:[1,1,0]
	v_mov_b32_e32 v145, v73
	v_mov_b32_e32 v159, v108
	v_pk_add_f32 v[144:145], v[144:145], v[158:159]
	v_and_b32_e32 v2, 64, v152
	v_pk_add_f32 v[142:143], v[142:143], v[144:145]
	v_add_u32_e32 v2, 64, v2
	v_add_f32_e32 v1, v142, v143
	v_xor_b32_e32 v73, 1, v152
	v_cmp_lt_i32_e32 vcc, v73, v2
	v_mov_b32_e32 v118, v121
	v_mov_b32_e32 v120, v122
	v_cndmask_b32_e32 v73, v152, v73, vcc
	v_lshlrev_b32_e32 v73, 2, v73
	ds_bpermute_b32 v73, v73, v1
	v_mov_b32_e32 v121, v124
	v_mov_b32_e32 v124, v123
	v_mov_b32_e32 v108, v111
	s_waitcnt lgkmcnt(0)
; __device__ __forceinline__ float* OUTP() { return (float*)IN(40); }
; __device__ __forceinline__ unsigned pk2(float lo, float hi) { f32x2c v = {lo, hi}; return __builtin_bit_cast(unsigned, __builtin_convertvector(v, bf16x2c)); }
; __device__ __forceinline__ float row_rstd(const f32x4 (&v)[8]) {
;     float s = 0.f;
; #pragma unroll
;     for (int j = 0; j < 8; ++j) s += (v[j][0] * v[j][0] + v[j][1] * v[j][1]) + (v[j][2] * v[j][2] + v[j][3] * v[j][3]);
;     return rsqrtf(wave_sum(s) * (1.f / D) + 1e-6f);
; __device__ __forceinline__ void row_pre(const Params& p, int layer) {
;     ...
;                 const float rs = row_rstd(dn);
; #pragma unroll
;                 for (int j = 0; j < 8; ++j) { const f32x4 g = *(const f32x4*)(gpost + 256 * j + 4 * lane); x[j] += dn[j] * rs * g; }
;                 if (r >= 0) {
; #pragma unroll
;                     for (int j = 0; j < 8; ++j) { if (layer == 4) *(f32x4*)(OUTP() + (size_t)m * D + 256 * j + 4 * lane) = x[j];
;                         else { u32x2 w; w.x = pk2(x[j][0], x[j][1]); w.y = pk2(x[j][2], x[j][3]); *(u32x2*)(Xnew + (size_t)m * D + 256 * j + 4 * lane) = w; } }
	v_add_f32_e32 v1, v1, v73
	v_xor_b32_e32 v73, 2, v152
	v_cmp_lt_i32_e32 vcc, v73, v2
	s_nop 1
	v_cndmask_b32_e32 v73, v152, v73, vcc
	v_lshlrev_b32_e32 v73, 2, v73
	ds_bpermute_b32 v73, v73, v1
	s_waitcnt lgkmcnt(0)
	v_add_f32_e32 v1, v1, v73
	v_xor_b32_e32 v73, 4, v152
	v_cmp_lt_i32_e32 vcc, v73, v2
	s_nop 1
	v_cndmask_b32_e32 v73, v152, v73, vcc
	v_lshlrev_b32_e32 v73, 2, v73
	ds_bpermute_b32 v73, v73, v1
	s_waitcnt lgkmcnt(0)
	v_add_f32_e32 v1, v1, v73
	v_xor_b32_e32 v73, 8, v152
	v_cmp_lt_i32_e32 vcc, v73, v2
	s_nop 1
	v_cndmask_b32_e32 v73, v152, v73, vcc
	v_lshlrev_b32_e32 v73, 2, v73
	ds_bpermute_b32 v73, v73, v1
	s_waitcnt lgkmcnt(0)
	v_add_f32_e32 v1, v1, v73
	v_xor_b32_e32 v73, 16, v152
	v_cmp_lt_i32_e32 vcc, v73, v2
	s_nop 1
	v_cndmask_b32_e32 v73, v152, v73, vcc
	v_lshlrev_b32_e32 v73, 2, v73
	ds_bpermute_b32 v73, v73, v1
	s_waitcnt lgkmcnt(0)
	v_add_f32_e32 v1, v1, v73
	v_xor_b32_e32 v73, 32, v152
	v_cmp_lt_i32_e32 vcc, v73, v2
	s_nop 1
	v_cndmask_b32_e32 v2, v152, v73, vcc
	v_lshlrev_b32_e32 v2, 2, v2
	ds_bpermute_b32 v2, v2, v1
	s_waitcnt lgkmcnt(0)
	v_add_f32_e32 v1, v1, v2
	v_fmamk_f32 v1, v1, 0x3a000000, v147
	v_cmp_gt_f32_e32 vcc, s29, v1
	v_mul_f32_e32 v2, 0x4b800000, v1
	s_nop 0
	v_cndmask_b32_e32 v1, v1, v2, vcc
	v_rsq_f32_e32 v1, v1
	s_nop 0
	v_mul_f32_e32 v2, 0x45800000, v1
	v_cndmask_b32_e32 v2, v1, v2, vcc
	v_pk_mul_f32 v[138:139], v[2:3], v[138:139] op_sel_hi:[0,1]
	v_pk_mul_f32 v[140:141], v[2:3], v[140:141] op_sel_hi:[0,1]
	v_pk_fma_f32 v[66:67], v[198:199], v[140:141], v[66:67]
	v_pk_fma_f32 v[64:65], v[196:197], v[138:139], v[64:65]
	v_mov_b32_e32 v142, v130
	v_mov_b32_e32 v143, v136
	v_pk_mul_f32 v[142:143], v[2:3], v[142:143] op_sel_hi:[0,1]
	v_mov_b32_e32 v136, v131
	v_pk_mul_f32 v[130:131], v[2:3], v[136:137] op_sel_hi:[0,1]
	v_pk_mul_f32 v[126:127], v[2:3], v[126:127] op_sel_hi:[0,1]
	v_pk_mul_f32 v[128:129], v[2:3], v[128:129] op_sel_hi:[0,1]
	v_pk_mul_f32 v[118:119], v[2:3], v[118:119] op_sel_hi:[0,1]
	v_pk_mul_f32 v[116:117], v[2:3], v[116:117] op_sel_hi:[0,1]
	v_pk_mul_f32 v[120:121], v[2:3], v[120:121] op_sel_hi:[0,1]
	v_pk_mul_f32 v[122:123], v[2:3], v[124:125] op_sel_hi:[0,1]
	v_pk_mul_f32 v[68:69], v[2:3], v[68:69] op_sel_hi:[0,1]
	v_pk_mul_f32 v[70:71], v[2:3], v[70:71] op_sel_hi:[0,1]
	v_pk_mul_f32 v[108:109], v[2:3], v[108:109] op_sel_hi:[0,1]
	v_pk_mul_f32 v[106:107], v[2:3], v[106:107] op_sel_hi:[0,1]
	v_pk_fma_f32 v[60:61], v[200:201], v[142:143], v[60:61]
	v_pk_fma_f32 v[62:63], v[202:203], v[130:131], v[62:63]
	v_pk_fma_f32 v[58:59], v[206:207], v[128:129], v[58:59]
	v_pk_fma_f32 v[56:57], v[204:205], v[126:127], v[56:57]
	v_pk_fma_f32 v[50:51], v[210:211], v[116:117], v[50:51]
	v_pk_fma_f32 v[48:49], v[208:209], v[118:119], v[48:49]
	v_pk_fma_f32 v[54:55], v[214:215], v[122:123], v[54:55]
	v_pk_fma_f32 v[52:53], v[212:213], v[120:121], v[52:53]
	v_mov_b32_e32 v121, v114
	v_mov_b32_e32 v114, v113
	v_mov_b32_e32 v120, v112
	v_pk_mul_f32 v[112:113], v[2:3], v[114:115] op_sel_hi:[0,1]
	v_pk_mul_f32 v[120:121], v[2:3], v[120:121] op_sel_hi:[0,1]
	v_pk_fma_f32 v[46:47], v[218:219], v[112:113], v[46:47]
	v_pk_fma_f32 v[44:45], v[216:217], v[120:121], v[44:45]
	v_pk_fma_f32 v[42:43], v[222:223], v[70:71], v[42:43]
	v_pk_fma_f32 v[40:41], v[220:221], v[68:69], v[40:41]
	v_pk_fma_f32 v[38:39], v[226:227], v[106:107], v[38:39]
	v_pk_fma_f32 v[36:37], v[224:225], v[108:109], v[36:37]
	s_cbranch_scc1 .LBB0_662
	s_lshl_b64 s[18:19], s[16:17], 11
	v_lshl_add_u64 v[68:69], s[18:19], 1, v[80:81]
	s_mov_b64 s[4:5], -1
	s_and_b64 vcc, exec, s[6:7]
	s_cbranch_vccz .LBB0_645
	v_cvt_pk_bf16_f32 v70, v64, v65
	v_cvt_pk_bf16_f32 v71, v66, v67
	global_store_dwordx2 v[68:69], v[70:71], off
	s_mov_b64 s[4:5], 0

; __device__ __forceinline__ void row_pre(const Params& p, int layer) {
;     ...
;         for (int r = rstart; r < 4; ++r) {
.LBB0_673:
	s_add_i32 s4, s37, 1
	s_cmp_gt_i32 s37, s101
	v_add_u32_e32 v0, 1, v0
	s_cbranch_scc1 .LBB0_626
	s_mov_b32 s37, s4
	s_add_i32 s16, s37, s34
	s_and_b64 vcc, exec, s[40:41]
	s_cbranch_vccnz .LBB0_634
	s_branch .LBB0_635
